# batched GEMM epilogues (mode 6 residual, mode 7 merge) and batched mid-loop gate rescale with counted vmcnt
# baseline (speedup 1.0000x reference)
; DEVI float bf_lo(unsigned u) { return __uint_as_float(u << 16); }
; DEVI float bf_hi(unsigned u) { return __uint_as_float(u & 0xffff0000u); }
; DEVI float sigmoidf_(float x) { return 1.f / (1.f + __expf(-x)); }
; DEVI u32x4 pack8(f32x4 a, f32x4 b) { u32x4 o; o.x = cvt_pk_bf16(a[0], a[1]); o.y = cvt_pk_bf16(a[2], a[3]); o.z = cvt_pk_bf16(b[0], b[1]); o.w = cvt_pk_bf16(b[2], b[3]); return o; }
; DEVI void gemm_epi(const GJob& jb, int row, int col, f32x4 v0, f32x4 v1) {
;   const int mode = jb.mode;
;   if (mode == 0) { *(u32x4*)((bf16_t*)jb.out + (size_t)row * jb.ldo + col) = pack8(v0, v1); }
;   else if (mode == 1) { float* p = (float*)jb.out + (size_t)row * jb.ldo + col; *(f32x4*)p = v0; *(f32x4*)(p + 4) = v1; }
;   else if (mode == 2) { f32x4 s0, s1; for (int i = 0; i < 4; ++i) { s0[i] = sigmoidf_(v0[i]); s1[i] = sigmoidf_(v1[i]); } *(u32x4*)((bf16_t*)jb.out + (size_t)row * jb.ldo + col) = pack8(s0, s1); }
;   else if (mode == 7) {
;     const u32x4 g = *(const u32x4*)((const bf16_t*)jb.aux + (size_t)row * NGATE + 2 * 2048 + col);
;     const f32x4 g0 = {bf_lo(g.x), bf_hi(g.x), bf_lo(g.y), bf_hi(g.y)}, g1 = {bf_lo(g.z), bf_hi(g.z), bf_lo(g.w), bf_hi(g.w)};
;     *(u32x4*)((bf16_t*)jb.out + (size_t)row * 2048 + col) = pack8(g0 * v0, g1 * v1);
; DEVI void gemm_tile(const GJob& jb, int brow, int bcol, unsigned char* shm_) {
;     ...
;   for (int ai = 0; ai < 2; ++ai)
; #pragma unroll
;     for (int m = 0; m < 4; ++m)
; #pragma unroll
;       for (int bj = 0; bj < 2; ++bj)
;         gemm_epi(jb, brow + ai * HALF + wr * 64 + m * 16 + fr, bcol + bj * HALF + wc * 32 + fq * 8, acc[ai][bj][m][0], acc[ai][bj][m][1]);
.LBB0_424:
	v_or_b32_e32 v0, s43, v159
	v_add_u32_e32 v132, s47, v0
	v_or_b32_e32 v0, s12, v158
	v_ashrrev_i32_e32 v133, 31, v132
	v_or_b32_e32 v130, s68, v0
	s_cmp_eq_u32 s71, 6
	s_cbranch_scc1 .Lepi6
	s_cmp_eq_u32 s71, 7
	s_cbranch_scc1 .Lepi7
	v_mad_i64_i32 v[136:137], s[0:1], v132, s33, 0
	v_lshlrev_b64 v[134:135], 12, v[132:133]
	s_mov_b64 s[12:13], -1
	s_mov_b64 s[10:11], 0
	s_cmp_lt_i32 s71, 2
	s_mov_b64 s[8:9], 0
	s_cbranch_scc1 .LBB0_433
	s_cmp_gt_i32 s71, 6
	s_cbranch_scc0 .LBB0_429
	s_cmp_eq_u32 s71, 7
	s_mov_b64 s[8:9], -1
	s_cbranch_scc0 .LBB0_428
	v_ashrrev_i32_e32 v131, 31, v130
	v_lshl_add_u64 v[138:139], s[94:95], 0, v[136:137]
	v_lshlrev_b64 v[142:143], 1, v[130:131]
	v_lshl_add_u64 v[138:139], v[138:139], 0, v[142:143]
	v_add_co_u32_e32 v138, vcc, 0x2000, v138
	v_lshl_add_u64 v[144:145], s[90:91], 0, v[134:135]
	s_nop 0
	v_addc_co_u32_e32 v139, vcc, 0, v139, vcc
	flat_load_dwordx4 v[138:141], v[138:139]
	v_lshl_add_u64 v[142:143], v[144:145], 0, v[142:143]
	s_mov_b64 s[8:9], 0
	s_waitcnt vmcnt(0) lgkmcnt(0)
	v_lshlrev_b32_e32 v144, 16, v138
	v_and_b32_e32 v145, 0xffff0000, v138
	v_lshlrev_b32_e32 v138, 16, v139
	v_and_b32_e32 v139, 0xffff0000, v139
	v_lshlrev_b32_e32 v146, 16, v140
	v_and_b32_e32 v147, 0xffff0000, v140
	v_lshlrev_b32_e32 v140, 16, v141
	v_and_b32_e32 v141, 0xffff0000, v141
	v_pk_mul_f32 v[148:149], v[128:129], v[138:139]
	v_pk_mul_f32 v[138:139], v[126:127], v[144:145]
	v_pk_mul_f32 v[144:145], v[124:125], v[140:141]
	v_pk_mul_f32 v[140:141], v[122:123], v[146:147]
	v_cvt_pk_bf16_f32 v138, v138, v139
	v_cvt_pk_bf16_f32 v139, v148, v149
	s_nop 0
	v_cvt_pk_bf16_f32 v140, v140, v141
	v_cvt_pk_bf16_f32 v141, v144, v145
	flat_store_dwordx4 v[142:143], v[138:141]

; DEVI float bf_lo(unsigned u) { return __uint_as_float(u << 16); }
; DEVI float bf_hi(unsigned u) { return __uint_as_float(u & 0xffff0000u); }
; DEVI u32x4 pack8(f32x4 a, f32x4 b) { u32x4 o; o.x = cvt_pk_bf16(a[0], a[1]); o.y = cvt_pk_bf16(a[2], a[3]); o.z = cvt_pk_bf16(b[0], b[1]); o.w = cvt_pk_bf16(b[2], b[3]); return o; }
; DEVI void gemm_epi(const GJob& jb, int row, int col, f32x4 v0, f32x4 v1) {
;     ...
;   else if (mode == 7) {
;     const u32x4 g = *(const u32x4*)((const bf16_t*)jb.aux + (size_t)row * NGATE + 2 * 2048 + col);
;     const f32x4 g0 = {bf_lo(g.x), bf_hi(g.x), bf_lo(g.y), bf_hi(g.y)}, g1 = {bf_lo(g.z), bf_hi(g.z), bf_lo(g.w), bf_hi(g.w)};
;     *(u32x4*)((bf16_t*)jb.out + (size_t)row * 2048 + col) = pack8(g0 * v0, g1 * v1);
; DEVI void gemm_tile(const GJob& jb, int brow, int bcol, unsigned char* shm_) {
;     ...
;   for (int ai = 0; ai < 2; ++ai)
; #pragma unroll
;     for (int m = 0; m < 4; ++m)
; #pragma unroll
;       for (int bj = 0; bj < 2; ++bj)
;         gemm_epi(jb, brow + ai * HALF + wr * 64 + m * 16 + fr, bcol + bj * HALF + wc * 32 + fq * 8, acc[ai][bj][m][0], acc[ai][bj][m][1]);
.Lepi7:
	v_mul_lo_u32 v242, v132, s33
	v_lshlrev_b32_e32 v243, 12, v132
	v_lshl_add_u32 v242, v130, 1, v242
	v_lshl_add_u32 v243, v130, 1, v243
	v_add_u32_e32 v242, 0x2000, v242
	s_mul_i32 s10, s33, 0
	v_add_u32_e32 v246, s10, v242
	global_load_dwordx4 v[142:145], v246, s[94:95] offset:0
	global_load_dwordx4 v[146:149], v246, s[94:95] offset:256
	s_mul_i32 s10, s33, 16
	v_add_u32_e32 v246, s10, v242
	global_load_dwordx4 v[150:153], v246, s[94:95] offset:0
	global_load_dwordx4 v[154:157], v246, s[94:95] offset:256
	s_mul_i32 s10, s33, 32
	v_add_u32_e32 v246, s10, v242
	global_load_dwordx4 v[194:197], v246, s[94:95] offset:0
	global_load_dwordx4 v[198:201], v246, s[94:95] offset:256
	s_waitcnt vmcnt(4)
	v_lshlrev_b32_e32 v226, 16, v142
	v_and_b32_e32 v227, 0xffff0000, v142
	v_lshlrev_b32_e32 v228, 16, v143
	v_and_b32_e32 v229, 0xffff0000, v143
	v_lshlrev_b32_e32 v230, 16, v144
	v_and_b32_e32 v231, 0xffff0000, v144
	v_lshlrev_b32_e32 v232, 16, v145
	v_and_b32_e32 v233, 0xffff0000, v145
	v_pk_mul_f32 v[226:227], v[126:127], v[226:227]
	v_pk_mul_f32 v[228:229], v[128:129], v[228:229]
	v_pk_mul_f32 v[230:231], v[122:123], v[230:231]
	v_pk_mul_f32 v[232:233], v[124:125], v[232:233]
	v_cvt_pk_bf16_f32 v142, v226, v227
	v_cvt_pk_bf16_f32 v143, v228, v229
	v_cvt_pk_bf16_f32 v144, v230, v231
	v_cvt_pk_bf16_f32 v145, v232, v233
	v_lshlrev_b32_e32 v226, 16, v146
	v_and_b32_e32 v227, 0xffff0000, v146
	v_lshlrev_b32_e32 v228, 16, v147
	v_and_b32_e32 v229, 0xffff0000, v147
	v_lshlrev_b32_e32 v230, 16, v148
	v_and_b32_e32 v231, 0xffff0000, v148
	v_lshlrev_b32_e32 v232, 16, v149
	v_and_b32_e32 v233, 0xffff0000, v149
	v_pk_mul_f32 v[226:227], v[118:119], v[226:227]
	v_pk_mul_f32 v[228:229], v[120:121], v[228:229]
	v_pk_mul_f32 v[230:231], v[114:115], v[230:231]
	v_pk_mul_f32 v[232:233], v[116:117], v[232:233]
	v_cvt_pk_bf16_f32 v146, v226, v227
	v_cvt_pk_bf16_f32 v147, v228, v229
	v_cvt_pk_bf16_f32 v148, v230, v231
	v_cvt_pk_bf16_f32 v149, v232, v233
	s_mov_b32 s11, 0x0
	v_add_u32_e32 v247, s11, v243
	global_store_dwordx4 v247, v[142:145], s[90:91] offset:0
	global_store_dwordx4 v247, v[146:149], s[90:91] offset:256
	s_mul_i32 s10, s33, 48
	v_add_u32_e32 v246, s10, v242
	global_load_dwordx4 v[142:145], v246, s[94:95] offset:0
	global_load_dwordx4 v[146:149], v246, s[94:95] offset:256
	s_waitcnt vmcnt(6)
	v_lshlrev_b32_e32 v226, 16, v150
	v_and_b32_e32 v227, 0xffff0000, v150
	v_lshlrev_b32_e32 v228, 16, v151
	v_and_b32_e32 v229, 0xffff0000, v151
	v_lshlrev_b32_e32 v230, 16, v152
	v_and_b32_e32 v231, 0xffff0000, v152
	v_lshlrev_b32_e32 v232, 16, v153
	v_and_b32_e32 v233, 0xffff0000, v153
	v_pk_mul_f32 v[226:227], v[110:111], v[226:227]
	v_pk_mul_f32 v[228:229], v[112:113], v[228:229]
	v_pk_mul_f32 v[230:231], v[106:107], v[230:231]
	v_pk_mul_f32 v[232:233], v[108:109], v[232:233]
	v_cvt_pk_bf16_f32 v150, v226, v227
	v_cvt_pk_bf16_f32 v151, v228, v229
	v_cvt_pk_bf16_f32 v152, v230, v231
	v_cvt_pk_bf16_f32 v153, v232, v233
	v_lshlrev_b32_e32 v226, 16, v154
	v_and_b32_e32 v227, 0xffff0000, v154
	v_lshlrev_b32_e32 v228, 16, v155
	v_and_b32_e32 v229, 0xffff0000, v155
	v_lshlrev_b32_e32 v230, 16, v156
	v_and_b32_e32 v231, 0xffff0000, v156
	v_lshlrev_b32_e32 v232, 16, v157
	v_and_b32_e32 v233, 0xffff0000, v157
	v_pk_mul_f32 v[226:227], v[102:103], v[226:227]
	v_pk_mul_f32 v[228:229], v[104:105], v[228:229]
	v_pk_mul_f32 v[230:231], v[98:99], v[230:231]
	v_pk_mul_f32 v[232:233], v[100:101], v[232:233]
	v_cvt_pk_bf16_f32 v154, v226, v227
	v_cvt_pk_bf16_f32 v155, v228, v229
	v_cvt_pk_bf16_f32 v156, v230, v231
	v_cvt_pk_bf16_f32 v157, v232, v233
	s_mov_b32 s11, 0x10000
	v_add_u32_e32 v247, s11, v243
	global_store_dwordx4 v247, v[150:153], s[90:91] offset:0
	global_store_dwordx4 v247, v[154:157], s[90:91] offset:256
	s_mul_i32 s10, s33, 128
	v_add_u32_e32 v246, s10, v242
	global_load_dwordx4 v[150:153], v246, s[94:95] offset:0
	global_load_dwordx4 v[154:157], v246, s[94:95] offset:256
	s_waitcnt vmcnt(8)
	v_lshlrev_b32_e32 v226, 16, v194
	v_and_b32_e32 v227, 0xffff0000, v194
	v_lshlrev_b32_e32 v228, 16, v195
	v_and_b32_e32 v229, 0xffff0000, v195
	v_lshlrev_b32_e32 v230, 16, v196
	v_and_b32_e32 v231, 0xffff0000, v196
	v_lshlrev_b32_e32 v232, 16, v197
	v_and_b32_e32 v233, 0xffff0000, v197
	v_pk_mul_f32 v[226:227], v[94:95], v[226:227]
	v_pk_mul_f32 v[228:229], v[96:97], v[228:229]
	v_pk_mul_f32 v[230:231], v[90:91], v[230:231]
	v_pk_mul_f32 v[232:233], v[92:93], v[232:233]
	v_cvt_pk_bf16_f32 v194, v226, v227
	v_cvt_pk_bf16_f32 v195, v228, v229
	v_cvt_pk_bf16_f32 v196, v230, v231
	v_cvt_pk_bf16_f32 v197, v232, v233
	v_lshlrev_b32_e32 v226, 16, v198
	v_and_b32_e32 v227, 0xffff0000, v198
	v_lshlrev_b32_e32 v228, 16, v199
	v_and_b32_e32 v229, 0xffff0000, v199
	v_lshlrev_b32_e32 v230, 16, v200
	v_and_b32_e32 v231, 0xffff0000, v200
	v_lshlrev_b32_e32 v232, 16, v201
	v_and_b32_e32 v233, 0xffff0000, v201
	v_pk_mul_f32 v[226:227], v[86:87], v[226:227]
	v_pk_mul_f32 v[228:229], v[88:89], v[228:229]
	v_pk_mul_f32 v[230:231], v[82:83], v[230:231]
	v_pk_mul_f32 v[232:233], v[84:85], v[232:233]
	v_cvt_pk_bf16_f32 v198, v226, v227
	v_cvt_pk_bf16_f32 v199, v228, v229
	v_cvt_pk_bf16_f32 v200, v230, v231
	v_cvt_pk_bf16_f32 v201, v232, v233
	s_mov_b32 s11, 0x20000
	v_add_u32_e32 v247, s11, v243
	global_store_dwordx4 v247, v[194:197], s[90:91] offset:0
	global_store_dwordx4 v247, v[198:201], s[90:91] offset:256
	s_mul_i32 s10, s33, 144
	v_add_u32_e32 v246, s10, v242
	global_load_dwordx4 v[194:197], v246, s[94:95] offset:0
	global_load_dwordx4 v[198:201], v246, s[94:95] offset:256
	s_waitcnt vmcnt(8)
; DEVI float bf_lo(unsigned u) { return __uint_as_float(u << 16); }
; DEVI float bf_hi(unsigned u) { return __uint_as_float(u & 0xffff0000u); }
; DEVI u32x4 pack8(f32x4 a, f32x4 b) { u32x4 o; o.x = cvt_pk_bf16(a[0], a[1]); o.y = cvt_pk_bf16(a[2], a[3]); o.z = cvt_pk_bf16(b[0], b[1]); o.w = cvt_pk_bf16(b[2], b[3]); return o; }
; DEVI void gemm_epi(const GJob& jb, int row, int col, f32x4 v0, f32x4 v1) {
;     ...
;   else if (mode == 7) {
;     const u32x4 g = *(const u32x4*)((const bf16_t*)jb.aux + (size_t)row * NGATE + 2 * 2048 + col);
;     const f32x4 g0 = {bf_lo(g.x), bf_hi(g.x), bf_lo(g.y), bf_hi(g.y)}, g1 = {bf_lo(g.z), bf_hi(g.z), bf_lo(g.w), bf_hi(g.w)};
;     *(u32x4*)((bf16_t*)jb.out + (size_t)row * 2048 + col) = pack8(g0 * v0, g1 * v1);
; DEVI void gemm_tile(const GJob& jb, int brow, int bcol, unsigned char* shm_) {
;     ...
;   for (int ai = 0; ai < 2; ++ai)
; #pragma unroll
;     for (int m = 0; m < 4; ++m)
; #pragma unroll
;       for (int bj = 0; bj < 2; ++bj)
;         gemm_epi(jb, brow + ai * HALF + wr * 64 + m * 16 + fr, bcol + bj * HALF + wc * 32 + fq * 8, acc[ai][bj][m][0], acc[ai][bj][m][1]);
	v_lshlrev_b32_e32 v226, 16, v142
	v_and_b32_e32 v227, 0xffff0000, v142
	v_lshlrev_b32_e32 v228, 16, v143
	v_and_b32_e32 v229, 0xffff0000, v143
	v_lshlrev_b32_e32 v230, 16, v144
	v_and_b32_e32 v231, 0xffff0000, v144
	v_lshlrev_b32_e32 v232, 16, v145
	v_and_b32_e32 v233, 0xffff0000, v145
	v_pk_mul_f32 v[226:227], v[78:79], v[226:227]
	v_pk_mul_f32 v[228:229], v[80:81], v[228:229]
	v_pk_mul_f32 v[230:231], v[74:75], v[230:231]
	v_pk_mul_f32 v[232:233], v[76:77], v[232:233]
	v_cvt_pk_bf16_f32 v142, v226, v227
	v_cvt_pk_bf16_f32 v143, v228, v229
	v_cvt_pk_bf16_f32 v144, v230, v231
	v_cvt_pk_bf16_f32 v145, v232, v233
	v_lshlrev_b32_e32 v226, 16, v146
	v_and_b32_e32 v227, 0xffff0000, v146
	v_lshlrev_b32_e32 v228, 16, v147
	v_and_b32_e32 v229, 0xffff0000, v147
	v_lshlrev_b32_e32 v230, 16, v148
	v_and_b32_e32 v231, 0xffff0000, v148
	v_lshlrev_b32_e32 v232, 16, v149
	v_and_b32_e32 v233, 0xffff0000, v149
	v_pk_mul_f32 v[226:227], v[70:71], v[226:227]
	v_pk_mul_f32 v[228:229], v[72:73], v[228:229]
	v_pk_mul_f32 v[230:231], v[66:67], v[230:231]
	v_pk_mul_f32 v[232:233], v[68:69], v[232:233]
	v_cvt_pk_bf16_f32 v146, v226, v227
	v_cvt_pk_bf16_f32 v147, v228, v229
	v_cvt_pk_bf16_f32 v148, v230, v231
	v_cvt_pk_bf16_f32 v149, v232, v233
	s_mov_b32 s11, 0x30000
	v_add_u32_e32 v247, s11, v243
	global_store_dwordx4 v247, v[142:145], s[90:91] offset:0
	global_store_dwordx4 v247, v[146:149], s[90:91] offset:256
	s_mul_i32 s10, s33, 160
	v_add_u32_e32 v246, s10, v242
	global_load_dwordx4 v[142:145], v246, s[94:95] offset:0
	global_load_dwordx4 v[146:149], v246, s[94:95] offset:256
	s_waitcnt vmcnt(8)
	v_lshlrev_b32_e32 v226, 16, v150
	v_and_b32_e32 v227, 0xffff0000, v150
	v_lshlrev_b32_e32 v228, 16, v151
	v_and_b32_e32 v229, 0xffff0000, v151
	v_lshlrev_b32_e32 v230, 16, v152
	v_and_b32_e32 v231, 0xffff0000, v152
	v_lshlrev_b32_e32 v232, 16, v153
	v_and_b32_e32 v233, 0xffff0000, v153
	v_pk_mul_f32 v[226:227], v[62:63], v[226:227]
	v_pk_mul_f32 v[228:229], v[64:65], v[228:229]
	v_pk_mul_f32 v[230:231], v[58:59], v[230:231]
	v_pk_mul_f32 v[232:233], v[60:61], v[232:233]
	v_cvt_pk_bf16_f32 v150, v226, v227
	v_cvt_pk_bf16_f32 v151, v228, v229
	v_cvt_pk_bf16_f32 v152, v230, v231
	v_cvt_pk_bf16_f32 v153, v232, v233
	v_lshlrev_b32_e32 v226, 16, v154
	v_and_b32_e32 v227, 0xffff0000, v154
	v_lshlrev_b32_e32 v228, 16, v155
	v_and_b32_e32 v229, 0xffff0000, v155
	v_lshlrev_b32_e32 v230, 16, v156
	v_and_b32_e32 v231, 0xffff0000, v156
	v_lshlrev_b32_e32 v232, 16, v157
	v_and_b32_e32 v233, 0xffff0000, v157
	v_pk_mul_f32 v[226:227], v[54:55], v[226:227]
	v_pk_mul_f32 v[228:229], v[56:57], v[228:229]
	v_pk_mul_f32 v[230:231], v[50:51], v[230:231]
	v_pk_mul_f32 v[232:233], v[52:53], v[232:233]
	v_cvt_pk_bf16_f32 v154, v226, v227
	v_cvt_pk_bf16_f32 v155, v228, v229
	v_cvt_pk_bf16_f32 v156, v230, v231
	v_cvt_pk_bf16_f32 v157, v232, v233
	s_mov_b32 s11, 0x80000
	v_add_u32_e32 v247, s11, v243
	global_store_dwordx4 v247, v[150:153], s[90:91] offset:0
	global_store_dwordx4 v247, v[154:157], s[90:91] offset:256
	s_mul_i32 s10, s33, 176
	v_add_u32_e32 v246, s10, v242
	global_load_dwordx4 v[150:153], v246, s[94:95] offset:0
	global_load_dwordx4 v[154:157], v246, s[94:95] offset:256
	s_waitcnt vmcnt(8)
; DEVI float bf_lo(unsigned u) { return __uint_as_float(u << 16); }
; DEVI float bf_hi(unsigned u) { return __uint_as_float(u & 0xffff0000u); }
; DEVI u32x4 pack8(f32x4 a, f32x4 b) { u32x4 o; o.x = cvt_pk_bf16(a[0], a[1]); o.y = cvt_pk_bf16(a[2], a[3]); o.z = cvt_pk_bf16(b[0], b[1]); o.w = cvt_pk_bf16(b[2], b[3]); return o; }
; DEVI void gemm_epi(const GJob& jb, int row, int col, f32x4 v0, f32x4 v1) {
;     ...
;   else if (mode == 7) {
;     const u32x4 g = *(const u32x4*)((const bf16_t*)jb.aux + (size_t)row * NGATE + 2 * 2048 + col);
;     const f32x4 g0 = {bf_lo(g.x), bf_hi(g.x), bf_lo(g.y), bf_hi(g.y)}, g1 = {bf_lo(g.z), bf_hi(g.z), bf_lo(g.w), bf_hi(g.w)};
;     *(u32x4*)((bf16_t*)jb.out + (size_t)row * 2048 + col) = pack8(g0 * v0, g1 * v1);
; DEVI void gemm_tile(const GJob& jb, int brow, int bcol, unsigned char* shm_) {
;     ...
;   for (int ai = 0; ai < 2; ++ai)
; #pragma unroll
;     for (int m = 0; m < 4; ++m)
; #pragma unroll
;       for (int bj = 0; bj < 2; ++bj)
;         gemm_epi(jb, brow + ai * HALF + wr * 64 + m * 16 + fr, bcol + bj * HALF + wc * 32 + fq * 8, acc[ai][bj][m][0], acc[ai][bj][m][1]);
	v_lshlrev_b32_e32 v226, 16, v194
	v_and_b32_e32 v227, 0xffff0000, v194
	v_lshlrev_b32_e32 v228, 16, v195
	v_and_b32_e32 v229, 0xffff0000, v195
	v_lshlrev_b32_e32 v230, 16, v196
	v_and_b32_e32 v231, 0xffff0000, v196
	v_lshlrev_b32_e32 v232, 16, v197
	v_and_b32_e32 v233, 0xffff0000, v197
	v_pk_mul_f32 v[226:227], v[46:47], v[226:227]
	v_pk_mul_f32 v[228:229], v[48:49], v[228:229]
	v_pk_mul_f32 v[230:231], v[42:43], v[230:231]
	v_pk_mul_f32 v[232:233], v[44:45], v[232:233]
	v_cvt_pk_bf16_f32 v194, v226, v227
	v_cvt_pk_bf16_f32 v195, v228, v229
	v_cvt_pk_bf16_f32 v196, v230, v231
	v_cvt_pk_bf16_f32 v197, v232, v233
	v_lshlrev_b32_e32 v226, 16, v198
	v_and_b32_e32 v227, 0xffff0000, v198
	v_lshlrev_b32_e32 v228, 16, v199
	v_and_b32_e32 v229, 0xffff0000, v199
	v_lshlrev_b32_e32 v230, 16, v200
	v_and_b32_e32 v231, 0xffff0000, v200
	v_lshlrev_b32_e32 v232, 16, v201
	v_and_b32_e32 v233, 0xffff0000, v201
	v_pk_mul_f32 v[226:227], v[38:39], v[226:227]
	v_pk_mul_f32 v[228:229], v[40:41], v[228:229]
	v_pk_mul_f32 v[230:231], v[34:35], v[230:231]
	v_pk_mul_f32 v[232:233], v[36:37], v[232:233]
	v_cvt_pk_bf16_f32 v198, v226, v227
	v_cvt_pk_bf16_f32 v199, v228, v229
	v_cvt_pk_bf16_f32 v200, v230, v231
	v_cvt_pk_bf16_f32 v201, v232, v233
	s_mov_b32 s11, 0x90000
	v_add_u32_e32 v247, s11, v243
	global_store_dwordx4 v247, v[194:197], s[90:91] offset:0
	global_store_dwordx4 v247, v[198:201], s[90:91] offset:256
	s_waitcnt vmcnt(6)
	v_lshlrev_b32_e32 v226, 16, v142
	v_and_b32_e32 v227, 0xffff0000, v142
	v_lshlrev_b32_e32 v228, 16, v143
	v_and_b32_e32 v229, 0xffff0000, v143
	v_lshlrev_b32_e32 v230, 16, v144
	v_and_b32_e32 v231, 0xffff0000, v144
	v_lshlrev_b32_e32 v232, 16, v145
	v_and_b32_e32 v233, 0xffff0000, v145
	v_pk_mul_f32 v[226:227], v[30:31], v[226:227]
	v_pk_mul_f32 v[228:229], v[32:33], v[228:229]
	v_pk_mul_f32 v[230:231], v[26:27], v[230:231]
	v_pk_mul_f32 v[232:233], v[28:29], v[232:233]
	v_cvt_pk_bf16_f32 v142, v226, v227
	v_cvt_pk_bf16_f32 v143, v228, v229
	v_cvt_pk_bf16_f32 v144, v230, v231
	v_cvt_pk_bf16_f32 v145, v232, v233
	v_lshlrev_b32_e32 v226, 16, v146
	v_and_b32_e32 v227, 0xffff0000, v146
	v_lshlrev_b32_e32 v228, 16, v147
	v_and_b32_e32 v229, 0xffff0000, v147
	v_lshlrev_b32_e32 v230, 16, v148
	v_and_b32_e32 v231, 0xffff0000, v148
	v_lshlrev_b32_e32 v232, 16, v149
	v_and_b32_e32 v233, 0xffff0000, v149
	v_pk_mul_f32 v[226:227], v[22:23], v[226:227]
	v_pk_mul_f32 v[228:229], v[24:25], v[228:229]
	v_pk_mul_f32 v[230:231], v[18:19], v[230:231]
	v_pk_mul_f32 v[232:233], v[20:21], v[232:233]
	v_cvt_pk_bf16_f32 v146, v226, v227
	v_cvt_pk_bf16_f32 v147, v228, v229
	v_cvt_pk_bf16_f32 v148, v230, v231
	v_cvt_pk_bf16_f32 v149, v232, v233
	s_mov_b32 s11, 0xa0000
	v_add_u32_e32 v247, s11, v243
	global_store_dwordx4 v247, v[142:145], s[90:91] offset:0
	global_store_dwordx4 v247, v[146:149], s[90:91] offset:256
	s_waitcnt vmcnt(4)
	v_lshlrev_b32_e32 v226, 16, v150
	v_and_b32_e32 v227, 0xffff0000, v150
	v_lshlrev_b32_e32 v228, 16, v151
	v_and_b32_e32 v229, 0xffff0000, v151
	v_lshlrev_b32_e32 v230, 16, v152
	v_and_b32_e32 v231, 0xffff0000, v152
	v_lshlrev_b32_e32 v232, 16, v153
	v_and_b32_e32 v233, 0xffff0000, v153
	v_pk_mul_f32 v[226:227], v[14:15], v[226:227]
	v_pk_mul_f32 v[228:229], v[16:17], v[228:229]
	v_pk_mul_f32 v[230:231], v[10:11], v[230:231]
	v_pk_mul_f32 v[232:233], v[12:13], v[232:233]
	v_cvt_pk_bf16_f32 v150, v226, v227
	v_cvt_pk_bf16_f32 v151, v228, v229
	v_cvt_pk_bf16_f32 v152, v230, v231
	v_cvt_pk_bf16_f32 v153, v232, v233
	v_lshlrev_b32_e32 v226, 16, v154
	v_and_b32_e32 v227, 0xffff0000, v154
	v_lshlrev_b32_e32 v228, 16, v155
	v_and_b32_e32 v229, 0xffff0000, v155
	v_lshlrev_b32_e32 v230, 16, v156
	v_and_b32_e32 v231, 0xffff0000, v156
	v_lshlrev_b32_e32 v232, 16, v157
	v_and_b32_e32 v233, 0xffff0000, v157
	v_pk_mul_f32 v[226:227], v[6:7], v[226:227]
	v_pk_mul_f32 v[228:229], v[8:9], v[228:229]
	v_pk_mul_f32 v[230:231], v[2:3], v[230:231]
	v_pk_mul_f32 v[232:233], v[4:5], v[232:233]
	v_cvt_pk_bf16_f32 v154, v226, v227
	v_cvt_pk_bf16_f32 v155, v228, v229
	v_cvt_pk_bf16_f32 v156, v230, v231
	v_cvt_pk_bf16_f32 v157, v232, v233
	s_mov_b32 s11, 0xb0000
	v_add_u32_e32 v247, s11, v243
	global_store_dwordx4 v247, v[150:153], s[90:91] offset:0
	global_store_dwordx4 v247, v[154:157], s[90:91] offset:256
	s_branch .LBB0_409
